# v21ab: v19 + in-proj epilogue row*ld as one 32-bit multiply + next-unit stage-0 loads via scalar bases (parity-padded)
# baseline (speedup 1.0000x reference)
; template <int MIX, bool DRY = false>
; __device__ __forceinline__ void attn_phase(LAS unsigned char* lds, const bf16_t* Qb, const bf16_t* Kb, const bf16_t* Vb, bf16_t* Gb, const float* qg, const float* kg, const float* sinks) {
;     ...
;     for (int g = 0; g < NG; ++g) { float mq = fabsf(qg[g * 64 + lane0]), mk = fabsf(kg[g * 64 + lane0]);
; #pragma unroll
;         for (int o = 1; o < 64; o <<= 1) { mq = fmaxf(mq, __shfl_xor(mq, o)); mk = fmaxf(mk, __shfl_xor(mk, o)); }
;         Mb = fmaxf(Mb, 8.0f * mq * mk); }
.LBB0_393:
	s_or_b64 exec, exec, s[4:5]
	v_readlane_b32 s6, v253, 35
	v_readlane_b32 s7, v253, 36
	s_mov_b64 s[4:5], -1
	s_and_b64 vcc, exec, s[36:37]
	s_waitcnt lgkmcnt(0)
	v_cndmask_b32_e64 v0, 0, 1, s[6:7]
	v_cmp_ne_u32_e64 s[6:7], 1, v0
	s_barrier
	s_nop 0
	v_writelane_b32 v251, s6, 53
	s_nop 1
	v_writelane_b32 v251, s7, 54
	s_cbranch_vccnz .LBB0_484
	v_readlane_b32 s4, v251, 50
	v_readlane_b32 s5, v251, 51
	s_mov_b32 s1, s5
	s_lshl_b64 s[4:5], s[0:1], 2
	v_mov_b32_e32 v202, v196
	v_ashrrev_i32_e32 v237, 4, v202
	v_lshlrev_b32_e32 v238, 2, v237
	v_and_b32_e32 v238, 4, v238
	v_xor_b32_e32 v237, v237, v202
	v_bitop3_b32 v237, v237, v238, 7 bitop3:0x6c
	v_ashrrev_i32_e32 v238, 3, v202
	v_lshlrev_b32_e32 v238, 7, v238
	v_lshl_or_b32 v237, v237, 4, v238
	v_add_u32_e32 v238, 0x1a800, v237
	v_add_u32_e32 v237, 0x10800, v237
	v_ashrrev_i32_e32 v239, 3, v202
	v_lshlrev_b32_e32 v240, 4, v202
	v_and_b32_e32 v240, 0x70, v240
	v_lshl_add_u32 v239, v239, 11, v240
	v_add_u32_e32 v240, 0x20000, v239
	v_add_u32_e32 v242, 0x10200, v239
	v_add_u32_e32 v243, 0x30200, v239
	v_add_u32_e32 v241, 0x40000, v239
	v_subrev_u32_e32 v244, 0xfe00, v239
	v_cmp_gt_i32_e32 vcc, 0x100, v202
	s_nop 1
	v_cndmask_b32_e32 v241, v244, v241, vcc
	v_ashrrev_i32_e32 v244, 3, v202
	v_lshlrev_b32_e32 v245, 4, v202
	v_and_b32_e32 v245, 0x70, v245
	v_lshl_add_u32 v244, v244, 9, v245
	s_add_u32 s0, s74, s4
	s_addc_u32 s1, s75, s5
	v_and_b32_e32 v0, 63, v202
	v_lshlrev_b32_e32 v0, 2, v0
	global_load_dword v1, v0, s[0:1]
	global_load_dword v2, v0, s[0:1] offset:256
	s_add_u32 s4, s76, s4
	s_addc_u32 s5, s77, s5
	global_load_dword v3, v0, s[4:5]
	global_load_dword v4, v0, s[4:5] offset:256
	global_load_dword v5, v0, s[4:5] offset:512
	s_nop 0
	global_load_dword v0, v0, s[0:1] offset:512
	v_and_b32_e32 v6, 64, v197
	v_xor_b32_e32 v7, 1, v197
	v_add_u32_e32 v6, 64, v6
	v_xor_b32_e32 v8, 2, v197
	v_cmp_lt_i32_e32 vcc, v7, v6
	v_xor_b32_e32 v9, 4, v197
	v_xor_b32_e32 v10, 8, v197
	v_cndmask_b32_e32 v7, v197, v7, vcc
	v_cmp_lt_i32_e32 vcc, v8, v6
	v_xor_b32_e32 v11, 16, v197
	v_xor_b32_e32 v12, 32, v197
	v_cndmask_b32_e32 v8, v197, v8, vcc
	v_cmp_lt_i32_e32 vcc, v9, v6
	v_lshlrev_b32_e32 v7, 2, v7
	v_lshlrev_b32_e32 v8, 2, v8
	v_cndmask_b32_e32 v9, v197, v9, vcc
	v_cmp_lt_i32_e32 vcc, v10, v6
	v_lshlrev_b32_e32 v9, 2, v9
	v_readlane_b32 s0, v251, 53
	v_cndmask_b32_e32 v10, v197, v10, vcc
	v_cmp_lt_i32_e32 vcc, v11, v6
	v_lshlrev_b32_e32 v10, 2, v10
	v_readlane_b32 s1, v251, 54
	v_cndmask_b32_e32 v11, v197, v11, vcc
	v_cmp_lt_i32_e32 vcc, v12, v6
	v_lshlrev_b32_e32 v11, 2, v11
	v_readfirstlane_b32 s4, v202
	v_cndmask_b32_e32 v6, v197, v12, vcc
	v_lshlrev_b32_e32 v12, 2, v6
	s_and_b64 vcc, exec, s[0:1]
	s_waitcnt vmcnt(0)
	v_and_b32_e32 v6, 0x7fffffff, v1
	s_waitcnt vmcnt(4)
	v_and_b32_e32 v13, 0x7fffffff, v2
	ds_bpermute_b32 v6, v7, v6
	ds_bpermute_b32 v13, v7, v13
	s_waitcnt vmcnt(3)
	v_and_b32_e32 v14, 0x7fffffff, v3
	s_waitcnt vmcnt(2)
	v_and_b32_e32 v15, 0x7fffffff, v4
	ds_bpermute_b32 v14, v7, v14
	ds_bpermute_b32 v15, v7, v15
	v_max_f32_e64 v1, |v1|, |v1|
	v_max_f32_e64 v2, |v2|, |v2|
	s_waitcnt vmcnt(0)
	v_and_b32_e32 v16, 0x7fffffff, v0
	s_waitcnt lgkmcnt(3)
	v_max_f32_e32 v6, v6, v6
	s_waitcnt lgkmcnt(2)
	v_max_f32_e32 v13, v13, v13
	v_and_b32_e32 v17, 0x7fffffff, v5
	ds_bpermute_b32 v16, v7, v16
	v_max_f32_e32 v1, v1, v6
	v_max_f32_e32 v2, v2, v13
	ds_bpermute_b32 v7, v7, v17
	s_waitcnt lgkmcnt(3)
	v_max_f32_e32 v6, v14, v14
	ds_bpermute_b32 v13, v8, v1
	s_waitcnt lgkmcnt(3)
	v_max_f32_e32 v14, v15, v15
	ds_bpermute_b32 v15, v8, v2
	v_max_f32_e64 v3, |v3|, |v3|
	v_max_f32_e64 v4, |v4|, |v4|
	v_max_f32_e64 v0, |v0|, |v0|
	s_waitcnt lgkmcnt(3)
	v_max_f32_e32 v16, v16, v16
	v_max_f32_e64 v5, |v5|, |v5|
	s_waitcnt lgkmcnt(2)
	v_max_f32_e32 v7, v7, v7
	v_max_f32_e32 v3, v3, v6
	v_max_f32_e32 v4, v4, v14
	v_max_f32_e32 v0, v0, v16
	s_waitcnt lgkmcnt(1)
	v_max_f32_e32 v13, v13, v13
	s_waitcnt lgkmcnt(0)
	v_max_f32_e32 v15, v15, v15
	v_max_f32_e32 v5, v5, v7
	ds_bpermute_b32 v6, v8, v3
	ds_bpermute_b32 v7, v8, v4
	ds_bpermute_b32 v14, v8, v0
	v_max_f32_e32 v1, v1, v13
	v_max_f32_e32 v2, v2, v15
	ds_bpermute_b32 v13, v9, v1
	ds_bpermute_b32 v15, v9, v2
	s_waitcnt lgkmcnt(4)
	v_max_f32_e32 v6, v6, v6
	s_waitcnt lgkmcnt(3)
	v_max_f32_e32 v7, v7, v7
	s_waitcnt lgkmcnt(2)
	v_max_f32_e32 v14, v14, v14
	v_max_f32_e32 v3, v3, v6
	v_max_f32_e32 v4, v4, v7
	v_max_f32_e32 v6, v0, v14
	s_waitcnt lgkmcnt(1)
	v_max_f32_e32 v13, v13, v13
	s_waitcnt lgkmcnt(0)
	v_max_f32_e32 v14, v15, v15
	ds_bpermute_b32 v0, v9, v3
	ds_bpermute_b32 v7, v9, v4
	v_max_f32_e32 v1, v1, v13
	v_max_f32_e32 v2, v2, v14
	ds_bpermute_b32 v13, v10, v1
	ds_bpermute_b32 v14, v10, v2
	s_waitcnt lgkmcnt(3)
	v_max_f32_e32 v0, v0, v0
	s_waitcnt lgkmcnt(2)
	v_max_f32_e32 v7, v7, v7
	v_max_f32_e32 v0, v3, v0
	v_max_f32_e32 v3, v4, v7
	s_waitcnt lgkmcnt(1)
	v_max_f32_e32 v13, v13, v13
	s_waitcnt lgkmcnt(0)
	v_max_f32_e32 v14, v14, v14
	ds_bpermute_b32 v8, v8, v5
	ds_bpermute_b32 v7, v10, v3
	v_max_f32_e32 v1, v1, v13
	v_max_f32_e32 v13, v2, v14
	ds_bpermute_b32 v14, v11, v13
	s_waitcnt lgkmcnt(2)
	v_max_f32_e32 v8, v8, v8
	s_waitcnt lgkmcnt(1)
	v_max_f32_e32 v7, v7, v7
	v_max_f32_e32 v7, v3, v7
	v_max_f32_e32 v5, v5, v8
	s_waitcnt lgkmcnt(0)
	v_max_f32_e32 v3, v14, v14
	ds_bpermute_b32 v14, v9, v6
	ds_bpermute_b32 v8, v9, v5
	v_max_f32_e32 v3, v13, v3
	ds_bpermute_b32 v9, v11, v7
	ds_bpermute_b32 v4, v10, v0
	s_waitcnt lgkmcnt(3)
	v_max_f32_e32 v13, v14, v14
	v_max_f32_e32 v6, v6, v13
	s_waitcnt lgkmcnt(2)
	v_max_f32_e32 v8, v8, v8
	ds_bpermute_b32 v13, v10, v6
	v_max_f32_e32 v8, v5, v8
	ds_bpermute_b32 v10, v10, v8
	s_waitcnt lgkmcnt(3)
	v_max_f32_e32 v5, v9, v9
	v_max_f32_e32 v5, v7, v5
	s_waitcnt lgkmcnt(1)
	v_max_f32_e32 v7, v13, v13
	v_max_f32_e32 v2, v4, v4
	v_max_f32_e32 v6, v6, v7
	s_waitcnt lgkmcnt(0)
	v_max_f32_e32 v7, v10, v10
	ds_bpermute_b32 v4, v11, v1
	v_max_f32_e32 v2, v0, v2
	ds_bpermute_b32 v10, v11, v6
	v_max_f32_e32 v8, v8, v7
	ds_bpermute_b32 v15, v11, v2
	ds_bpermute_b32 v13, v11, v8
	s_waitcnt lgkmcnt(3)
	v_max_f32_e32 v0, v4, v4
	s_waitcnt lgkmcnt(2)
	v_max_f32_e32 v7, v10, v10
	v_max_f32_e32 v0, v1, v0
	s_waitcnt lgkmcnt(1)
	v_max_f32_e32 v1, v15, v15
	v_max_f32_e32 v7, v6, v7
	s_waitcnt lgkmcnt(0)
	v_max_f32_e32 v6, v13, v13
	v_max_f32_e32 v1, v2, v1
	v_max_f32_e32 v6, v8, v6
	ds_bpermute_b32 v4, v12, v0
	ds_bpermute_b32 v2, v12, v1
	ds_bpermute_b32 v11, v12, v3
	ds_bpermute_b32 v9, v12, v5
	ds_bpermute_b32 v10, v12, v7
	ds_bpermute_b32 v8, v12, v6
	s_cbranch_vccnz .LBB0_404
; template <int MIX, bool DRY = false>
; __device__ __forceinline__ void attn_phase(LAS unsigned char* lds, const bf16_t* Qb, const bf16_t* Kb, const bf16_t* Vb, bf16_t* Gb, const float* qg, const float* kg, const float* sinks) {
;     ...
;     if ((PF || MIX == 1) && (int)blockIdx.x < NUNITS) STAGE_LOAD(blockIdx.x, 0)
;     if (MIX == 1 && (int)blockIdx.x < NUNITS) STAGE_STORE(0)
	v_mov_b32_e32 v12, v202
	v_readlane_b32 s0, v253, 41
	v_ashrrev_i32_e32 v20, 3, v12
	v_lshlrev_b32_e32 v12, 4, v12
	v_and_b32_e32 v112, 0x70, v12
	v_readlane_b32 s1, v253, 42
	v_min_i32_e32 v16, 0xff, v20
	v_readlane_b32 s6, v253, 50
	v_lshl_add_u64 v[12:13], s[0:1], 0, v[112:113]
	v_readlane_b32 s0, v253, 43
	v_readlane_b32 s1, v253, 44
	v_readlane_b32 s7, v253, 51
	s_nop 0
	v_lshl_add_u64 v[14:15], s[0:1], 0, v[112:113]
	v_readlane_b32 s0, v253, 45
	s_nop 1
	v_add_u32_e32 v16, s0, v16
	v_ashrrev_i32_e32 v17, 31, v16
	v_lshlrev_b64 v[16:17], 8, v[16:17]
	v_lshl_add_u64 v[16:17], v[16:17], 0, s[6:7]
	v_lshlrev_b64 v[16:17], 1, v[16:17]
	v_lshl_add_u64 v[18:19], v[12:13], 0, v[16:17]
	v_lshl_add_u64 v[16:17], v[14:15], 0, v[16:17]
	global_load_dwordx4 v[114:117], v[18:19], off
	global_load_dwordx4 v[118:121], v[16:17], off
	v_min_i32_e32 v16, 0xbf, v20
	v_readlane_b32 s0, v253, 46
	s_nop 1
	v_add_u32_e32 v16, s0, v16
	v_ashrrev_i32_e32 v17, 31, v16
	v_lshlrev_b64 v[16:17], 8, v[16:17]
	v_lshl_add_u64 v[16:17], v[16:17], 0, s[6:7]
	v_lshlrev_b64 v[16:17], 1, v[16:17]
	v_lshl_add_u64 v[18:19], v[12:13], 0, v[16:17]
	v_lshl_add_u64 v[16:17], v[14:15], 0, v[16:17]
	global_load_dwordx4 v[122:125], v[18:19], off
	global_load_dwordx4 v[126:129], v[16:17], off
	v_min_i32_e32 v16, 0x7f, v20
	v_readlane_b32 s0, v253, 48
	s_nop 1
	v_add_u32_e32 v16, s0, v16
	v_ashrrev_i32_e32 v17, 31, v16
	v_lshlrev_b64 v[16:17], 8, v[16:17]
	v_lshl_add_u64 v[16:17], v[16:17], 0, s[6:7]
	v_lshlrev_b64 v[16:17], 1, v[16:17]
	v_lshl_add_u64 v[18:19], v[12:13], 0, v[16:17]
	v_lshl_add_u64 v[16:17], v[14:15], 0, v[16:17]
	global_load_dwordx4 v[130:133], v[18:19], off
	global_load_dwordx4 v[134:137], v[16:17], off
	v_min_i32_e32 v16, 63, v20
	v_readlane_b32 s0, v253, 47
	s_nop 1
	v_add_u32_e32 v16, s0, v16
	v_ashrrev_i32_e32 v17, 31, v16
	v_lshlrev_b64 v[16:17], 8, v[16:17]
	v_lshl_add_u64 v[16:17], v[16:17], 0, s[6:7]
	v_lshlrev_b64 v[16:17], 1, v[16:17]
	v_lshl_add_u64 v[18:19], v[12:13], 0, v[16:17]
	v_lshl_add_u64 v[16:17], v[14:15], 0, v[16:17]
	global_load_dwordx4 v[138:141], v[18:19], off
	global_load_dwordx4 v[142:145], v[16:17], off
	v_min_i32_e32 v16, -1, v20
	v_readlane_b32 s0, v253, 49
	s_nop 1
	v_add_u32_e32 v16, s0, v16
	v_ashrrev_i32_e32 v17, 31, v16
	v_lshlrev_b64 v[16:17], 8, v[16:17]
	v_lshl_add_u64 v[16:17], v[16:17], 0, s[6:7]
	v_lshlrev_b64 v[16:17], 1, v[16:17]
	v_lshl_add_u64 v[12:13], v[12:13], 0, v[16:17]
	v_lshl_add_u64 v[14:15], v[14:15], 0, v[16:17]
	global_load_dwordx4 v[146:149], v[12:13], off
	global_load_dwordx4 v[150:153], v[14:15], off
	v_mov_b32_e32 v12, v202
	s_movk_i32 s0, 0x100
	v_ashrrev_i32_e32 v13, 3, v12
	v_cmp_gt_i32_e32 vcc, s0, v13
	s_and_saveexec_b64 s[0:1], vcc
	s_cbranch_execz .LBB0_397
	v_ashrrev_i32_e32 v15, 4, v12
	v_lshlrev_b32_e32 v16, 2, v15
	v_and_b32_e32 v16, 4, v16
	v_xor_b32_e32 v15, v15, v12
	v_lshlrev_b32_e32 v14, 7, v13
	v_bitop3_b32 v15, v15, v16, 7 bitop3:0x6c
	v_lshl_or_b32 v14, v15, 4, v14
	v_add_u32_e32 v14, 0, v14
	v_add_u32_e32 v15, 0x10800, v14
	v_add_u32_e32 v14, 0x1a800, v14
	s_waitcnt vmcnt(9)
	ds_write_b128 v15, v[114:117]
	s_waitcnt vmcnt(8)
	ds_write_b128 v14, v[118:121]

; #define LAS __attribute__((address_space(3)))
; __device__ __forceinline__ unsigned pkbf(float lo, float hi) { f32x2v v = {lo, hi}; return __builtin_bit_cast(unsigned, __builtin_convertvector(v, bf2_t)); }
; __device__ __forceinline__ float bflo(unsigned w) { return __uint_as_float(w << 16); }
; __device__ __forceinline__ float bfhi(unsigned w) { return __uint_as_float(w & 0xffff0000u); }
; template <int MIX, bool DRY = false>
; __device__ __forceinline__ void attn_phase(LAS unsigned char* lds, const bf16_t* Qb, const bf16_t* Kb, const bf16_t* Vb, bf16_t* Gb, const float* qg, const float* kg, const float* sinks) {
;     ...
;             const bool more = unit + (int)gridDim.x < NUNITS;
;             STAGE_LOAD(more ? unit + (int)gridDim.x : unit, 0)
; #pragma unroll 4
;             for (int it = 0; it < (DRY ? 0 : 8); ++it) {
;                 const int item = it * 512 + tidu, row = item >> 3, dg = item & 7, hr = row / CT, tl = row % CT;
;                 const int f = ((tl >> 1) ^ (tl >> 4) ^ (hr << 2)) & 15, head = kvh * REP + hr;
;                 const LAS unsigned char* orow = Oacc + row * 128;
;                 const u32x2 o0 = *(const LAS u32x2*)(orow + (((2 * dg) ^ f) << 3)), o1 = *(const LAS u32x2*)(orow + (((2 * dg + 1) ^ f) << 3));
;                 const float inv = 1.0f / lacc[row];
;                 u32x4* gp = (u32x4*)(Gb + (rowb + t0 + tl) * 1024 + head * 64 + 8 * dg);
;                 const u32x4 gv = *gp;
;                 u32x4 w;
;                 w.x = pkbf(bflo(o0.x) * inv * bflo(gv.x), bfhi(o0.x) * inv * bfhi(gv.x)); w.y = pkbf(bflo(o0.y) * inv * bflo(gv.y), bfhi(o0.y) * inv * bfhi(gv.y));
;                 w.z = pkbf(bflo(o1.x) * inv * bflo(gv.z), bfhi(o1.x) * inv * bfhi(gv.z)); w.w = pkbf(bflo(o1.y) * inv * bflo(gv.w), bfhi(o1.y) * inv * bfhi(gv.w));
;                 *gp = w;
;             }
.LBB0_469:
	v_readlane_b32 s7, v250, 1
	s_add_i32 s6, s7, s80
	s_cmpk_lt_i32 s6, 0x400
	s_cselect_b64 s[0:1], -1, 0
	s_and_b64 s[4:5], s[0:1], exec
	s_cselect_b32 s7, s6, s7
	s_ashr_i32 s4, s7, 3
	s_andn2_b32 s4, s4, 31
	v_readlane_b32 s5, v250, 5
	s_add_i32 s4, s4, s5
	v_readlane_b32 s5, v250, 4
	s_or_b32 s8, s5, s4
	v_readlane_b32 s4, v253, 39
	v_readlane_b32 s5, v253, 40
	s_and_b64 s[4:5], s[4:5], exec
	s_cselect_b32 s4, s8, s7
	s_ashr_i32 s5, s4, 31
	s_lshr_b32 s7, s5, 27
	s_add_i32 s7, s4, s7
	s_ashr_i32 s8, s7, 5
	s_lshr_b32 s9, s8, 30
	s_add_i32 s9, s8, s9
	s_and_b32 s9, s9, 0x3fffffc
	s_and_b32 s7, s7, 0x1ffffe0
	s_sub_i32 s8, s8, s9
	s_lshr_b32 s5, s5, 25
	s_sub_i32 s7, s4, s7
	s_add_i32 s4, s4, s5
	s_lshl_b32 s8, s8, 6
	s_ashr_i32 s4, s4, 7
	s_ashr_i32 s9, s8, 31
	s_lshl_b32 s7, s7, 7
	s_ashr_i32 s5, s4, 31
	s_lshl_b64 s[8:9], s[8:9], 1
	v_readlane_b32 s10, v253, 56
	v_readlane_b32 s11, v253, 57
	s_add_u32 s10, s10, s8
	s_addc_u32 s11, s11, s9
	v_readlane_b32 s12, v253, 60
	v_mov_b32_e32 v16, v202
	s_waitcnt lgkmcnt(0)
	s_barrier
	v_readlane_b32 s13, v253, 61
	s_add_u32 s8, s12, s8
	s_addc_u32 s9, s13, s9
	s_add_i32 s12, s7, 0xffffff80
	s_ashr_i32 s13, s12, 31
	s_lshl_b64 s[12:13], s[12:13], 9
	s_lshl_b64 s[4:5], s[4:5], 21
	s_add_u32 s4, s4, s12
	s_addc_u32 s5, s5, s13
	s_add_u32 s10, s10, s4
	s_addc_u32 s11, s11, s5
	s_add_u32 s8, s8, s4
	s_addc_u32 s9, s9, s5
	global_load_dwordx4 v[114:117], v244, s[10:11]
	global_load_dwordx4 v[118:121], v244, s[8:9]
	s_add_u32 s10, s10, 0x8000
	s_addc_u32 s11, s11, 0
	s_add_u32 s8, s8, 0x8000
	s_addc_u32 s9, s9, 0
	global_load_dwordx4 v[122:125], v244, s[10:11]
	global_load_dwordx4 v[126:129], v244, s[8:9]
	s_add_u32 s10, s10, 0x8000
	s_addc_u32 s11, s11, 0
	s_add_u32 s8, s8, 0x8000
	s_addc_u32 s9, s9, 0
	global_load_dwordx4 v[130:133], v244, s[10:11]
	global_load_dwordx4 v[134:137], v244, s[8:9]
	s_add_u32 s10, s10, 0x8000
	s_addc_u32 s11, s11, 0
	s_add_u32 s8, s8, 0x8000
	s_addc_u32 s9, s9, 0
	global_load_dwordx4 v[138:141], v244, s[10:11]
	global_load_dwordx4 v[142:145], v244, s[8:9]
	global_load_dwordx4 v[146:149], v244, s[10:11]
	global_load_dwordx4 v[150:153], v244, s[8:9]
	s_nop 0
	v_lshlrev_b32_e32 v23, 1, v217
	v_readlane_b32 s10, v251, 17
	v_or_b32_e32 v24, 1, v23
	s_mov_b32 s4, 0
	s_waitcnt vmcnt(13)
	v_lshlrev_b64 v[16:17], 1, v[182:183]
	v_readlane_b32 s11, v251, 18
	v_lshrrev_b32_e32 v25, 3, v203
	v_lshlrev_b32_e32 v26, 7, v25
	v_lshlrev_b32_e32 v27, 2, v25
	v_add_u32_e32 v27, 0x10000, v27
	v_lshrrev_b32_e32 v28, 1, v25
	v_lshrrev_b32_e32 v29, 4, v25
	v_xor_b32_e32 v28, v28, v29
	v_and_b32_e32 v28, 15, v28
	v_xor_b32_e32 v28, v28, v23
	v_mov_b32_e32 v32, v25
	v_mov_b32_e32 v33, 0
	v_lshl_add_u64 v[30:31], s[82:83], 0, v[32:33]
	v_lshlrev_b64 v[30:31], 11, v[30:31]
	v_lshl_add_u64 v[30:31], s[10:11], 0, v[30:31]
	v_mov_b32_e32 v34, s91
	v_mov_b32_e32 v35, 0
	v_lshl_add_u64 v[30:31], v[34:35], 1, v[30:31]
	v_lshl_add_u64 v[30:31], v[30:31], 0, v[16:17]
	v_mov_b32_e32 v38, 0x20000
	v_mov_b32_e32 v39, 0
	v_lshl_add_u64 v[36:37], v[30:31], 0, v[38:39]
	global_load_dwordx4 v[40:43], v[30:31], off
	global_load_dwordx4 v[44:47], v[36:37], off
	global_load_dwordx4 v[48:51], v[30:31], off offset:128
	global_load_dwordx4 v[52:55], v[36:37], off offset:128
	global_load_dwordx4 v[56:59], v[30:31], off offset:256
	global_load_dwordx4 v[60:63], v[36:37], off offset:256
	global_load_dwordx4 v[64:67], v[30:31], off offset:384
	global_load_dwordx4 v[68:71], v[36:37], off offset:384
	v_lshl_add_u32 v83, v28, 3, v26
	ds_read_b64 v[72:73], v83
	v_xor_b32_e32 v84, 1, v28
	v_lshl_add_u32 v84, v84, 3, v26
	ds_read_b64 v[74:75], v84
	ds_read_b32 v76, v27
	v_xor_b32_e32 v83, 4, v28
	v_lshl_add_u32 v83, v83, 3, v26
	ds_read_b64 v[78:79], v83 offset:8192
	v_xor_b32_e32 v84, 5, v28
	v_lshl_add_u32 v84, v84, 3, v26
	ds_read_b64 v[80:81], v84 offset:8192
	ds_read_b32 v82, v27 offset:256
	s_waitcnt lgkmcnt(3)
	v_div_scale_f32 v154, s[8:9], v76, v76, 1.0
	v_rcp_f32_e32 v155, v154
	v_lshlrev_b32_e32 v88, 16, v72
	v_and_b32_e32 v89, 0xffff0000, v72
	v_fma_f32 v156, -v154, v155, 1.0
	v_fmac_f32_e32 v155, v156, v155
	v_div_scale_f32 v156, vcc, 1.0, v76, 1.0
	v_mul_f32_e32 v157, v156, v155
	v_fma_f32 v158, -v154, v157, v156
	v_fmac_f32_e32 v157, v158, v155
	v_fma_f32 v154, -v154, v157, v156
	v_div_fmas_f32 v154, v154, v155, v157
	v_div_fixup_f32 v160, v154, v76, 1.0
	v_lshlrev_b32_e32 v90, 16, v73
	v_and_b32_e32 v91, 0xffff0000, v73
	v_lshlrev_b32_e32 v92, 16, v74
	v_and_b32_e32 v93, 0xffff0000, v74
	v_lshlrev_b32_e32 v94, 16, v75
	v_and_b32_e32 v95, 0xffff0000, v75
	v_pk_mul_f32 v[88:89], v[160:161], v[88:89] op_sel_hi:[0,1]
	v_pk_mul_f32 v[90:91], v[160:161], v[90:91] op_sel_hi:[0,1]
	v_pk_mul_f32 v[92:93], v[160:161], v[92:93] op_sel_hi:[0,1]
	v_pk_mul_f32 v[94:95], v[160:161], v[94:95] op_sel_hi:[0,1]
	s_waitcnt vmcnt(7)
	v_lshlrev_b32_e32 v96, 16, v40
	v_and_b32_e32 v97, 0xffff0000, v40
	v_pk_mul_f32 v[88:89], v[88:89], v[96:97]
	v_lshlrev_b32_e32 v96, 16, v41
	v_and_b32_e32 v97, 0xffff0000, v41
	v_pk_mul_f32 v[90:91], v[90:91], v[96:97]
	v_lshlrev_b32_e32 v96, 16, v42
	v_and_b32_e32 v97, 0xffff0000, v42
	v_pk_mul_f32 v[92:93], v[92:93], v[96:97]
	v_lshlrev_b32_e32 v96, 16, v43
	v_and_b32_e32 v97, 0xffff0000, v43
	v_pk_mul_f32 v[94:95], v[94:95], v[96:97]
	v_cvt_pk_bf16_f32 v100, v88, v89
	v_cvt_pk_bf16_f32 v101, v90, v91
	v_cvt_pk_bf16_f32 v102, v92, v93
	v_cvt_pk_bf16_f32 v103, v94, v95
	global_store_dwordx4 v[30:31], v[100:103], off
	v_xor_b32_e32 v83, 4, v28
	v_lshl_add_u32 v83, v83, 3, v26
	ds_read_b64 v[72:73], v83 offset:16384
	v_xor_b32_e32 v84, 5, v28
	v_lshl_add_u32 v84, v84, 3, v26
	ds_read_b64 v[74:75], v84 offset:16384
	ds_read_b32 v76, v27 offset:512
	s_waitcnt lgkmcnt(3)
; #define LAS __attribute__((address_space(3)))
; __device__ __forceinline__ unsigned pkbf(float lo, float hi) { f32x2v v = {lo, hi}; return __builtin_bit_cast(unsigned, __builtin_convertvector(v, bf2_t)); }
; __device__ __forceinline__ float bflo(unsigned w) { return __uint_as_float(w << 16); }
; __device__ __forceinline__ float bfhi(unsigned w) { return __uint_as_float(w & 0xffff0000u); }
; template <int MIX, bool DRY = false>
; __device__ __forceinline__ void attn_phase(LAS unsigned char* lds, const bf16_t* Qb, const bf16_t* Kb, const bf16_t* Vb, bf16_t* Gb, const float* qg, const float* kg, const float* sinks) {
;     ...
;                 const int item = it * 512 + tidu, row = item >> 3, dg = item & 7, hr = row / CT, tl = row % CT;
;                 const int f = ((tl >> 1) ^ (tl >> 4) ^ (hr << 2)) & 15, head = kvh * REP + hr;
;                 const LAS unsigned char* orow = Oacc + row * 128;
;                 const u32x2 o0 = *(const LAS u32x2*)(orow + (((2 * dg) ^ f) << 3)), o1 = *(const LAS u32x2*)(orow + (((2 * dg + 1) ^ f) << 3));
;                 const float inv = 1.0f / lacc[row];
;                 u32x4* gp = (u32x4*)(Gb + (rowb + t0 + tl) * 1024 + head * 64 + 8 * dg);
;                 const u32x4 gv = *gp;
;                 u32x4 w;
;                 w.x = pkbf(bflo(o0.x) * inv * bflo(gv.x), bfhi(o0.x) * inv * bfhi(gv.x)); w.y = pkbf(bflo(o0.y) * inv * bflo(gv.y), bfhi(o0.y) * inv * bfhi(gv.y));
;                 w.z = pkbf(bflo(o1.x) * inv * bflo(gv.z), bfhi(o1.x) * inv * bfhi(gv.z)); w.w = pkbf(bflo(o1.y) * inv * bflo(gv.w), bfhi(o1.y) * inv * bfhi(gv.w));
;                 *gp = w;
;             }
	v_div_scale_f32 v154, s[8:9], v82, v82, 1.0
	v_rcp_f32_e32 v155, v154
	v_lshlrev_b32_e32 v88, 16, v78
	v_and_b32_e32 v89, 0xffff0000, v78
	v_fma_f32 v156, -v154, v155, 1.0
	v_fmac_f32_e32 v155, v156, v155
	v_div_scale_f32 v156, vcc, 1.0, v82, 1.0
	v_mul_f32_e32 v157, v156, v155
	v_fma_f32 v158, -v154, v157, v156
	v_fmac_f32_e32 v157, v158, v155
	v_fma_f32 v154, -v154, v157, v156
	v_div_fmas_f32 v154, v154, v155, v157
	v_div_fixup_f32 v160, v154, v82, 1.0
	v_lshlrev_b32_e32 v90, 16, v79
	v_and_b32_e32 v91, 0xffff0000, v79
	v_lshlrev_b32_e32 v92, 16, v80
	v_and_b32_e32 v93, 0xffff0000, v80
	v_lshlrev_b32_e32 v94, 16, v81
	v_and_b32_e32 v95, 0xffff0000, v81
	v_pk_mul_f32 v[88:89], v[160:161], v[88:89] op_sel_hi:[0,1]
	v_pk_mul_f32 v[90:91], v[160:161], v[90:91] op_sel_hi:[0,1]
	v_pk_mul_f32 v[92:93], v[160:161], v[92:93] op_sel_hi:[0,1]
	v_pk_mul_f32 v[94:95], v[160:161], v[94:95] op_sel_hi:[0,1]
	s_waitcnt vmcnt(7)
	v_lshlrev_b32_e32 v96, 16, v44
	v_and_b32_e32 v97, 0xffff0000, v44
	v_pk_mul_f32 v[88:89], v[88:89], v[96:97]
	v_lshlrev_b32_e32 v96, 16, v45
	v_and_b32_e32 v97, 0xffff0000, v45
	v_pk_mul_f32 v[90:91], v[90:91], v[96:97]
	v_lshlrev_b32_e32 v96, 16, v46
	v_and_b32_e32 v97, 0xffff0000, v46
	v_pk_mul_f32 v[92:93], v[92:93], v[96:97]
	v_lshlrev_b32_e32 v96, 16, v47
	v_and_b32_e32 v97, 0xffff0000, v47
	v_pk_mul_f32 v[94:95], v[94:95], v[96:97]
	v_cvt_pk_bf16_f32 v104, v88, v89
	v_cvt_pk_bf16_f32 v105, v90, v91
	v_cvt_pk_bf16_f32 v106, v92, v93
	v_cvt_pk_bf16_f32 v107, v94, v95
	global_store_dwordx4 v[36:37], v[104:107], off
	v_lshl_add_u32 v83, v28, 3, v26
	ds_read_b64 v[78:79], v83 offset:24576
	v_xor_b32_e32 v84, 1, v28
	v_lshl_add_u32 v84, v84, 3, v26
	ds_read_b64 v[80:81], v84 offset:24576
	ds_read_b32 v82, v27 offset:768
	s_waitcnt lgkmcnt(3)
	v_div_scale_f32 v154, s[8:9], v76, v76, 1.0
	v_rcp_f32_e32 v155, v154
	v_lshlrev_b32_e32 v88, 16, v72
	v_and_b32_e32 v89, 0xffff0000, v72
	v_fma_f32 v156, -v154, v155, 1.0
	v_fmac_f32_e32 v155, v156, v155
	v_div_scale_f32 v156, vcc, 1.0, v76, 1.0
	v_mul_f32_e32 v157, v156, v155
	v_fma_f32 v158, -v154, v157, v156
	v_fmac_f32_e32 v157, v158, v155
	v_fma_f32 v154, -v154, v157, v156
	v_div_fmas_f32 v154, v154, v155, v157
	v_div_fixup_f32 v160, v154, v76, 1.0
	v_lshlrev_b32_e32 v90, 16, v73
	v_and_b32_e32 v91, 0xffff0000, v73
	v_lshlrev_b32_e32 v92, 16, v74
	v_and_b32_e32 v93, 0xffff0000, v74
	v_lshlrev_b32_e32 v94, 16, v75
	v_and_b32_e32 v95, 0xffff0000, v75
	v_pk_mul_f32 v[88:89], v[160:161], v[88:89] op_sel_hi:[0,1]
	v_pk_mul_f32 v[90:91], v[160:161], v[90:91] op_sel_hi:[0,1]
	v_pk_mul_f32 v[92:93], v[160:161], v[92:93] op_sel_hi:[0,1]
	v_pk_mul_f32 v[94:95], v[160:161], v[94:95] op_sel_hi:[0,1]
	s_waitcnt vmcnt(7)
	v_lshlrev_b32_e32 v96, 16, v48
	v_and_b32_e32 v97, 0xffff0000, v48
	v_pk_mul_f32 v[88:89], v[88:89], v[96:97]
	v_lshlrev_b32_e32 v96, 16, v49
	v_and_b32_e32 v97, 0xffff0000, v49
	v_pk_mul_f32 v[90:91], v[90:91], v[96:97]
	v_lshlrev_b32_e32 v96, 16, v50
	v_and_b32_e32 v97, 0xffff0000, v50
	v_pk_mul_f32 v[92:93], v[92:93], v[96:97]
	v_lshlrev_b32_e32 v96, 16, v51
	v_and_b32_e32 v97, 0xffff0000, v51
	v_pk_mul_f32 v[94:95], v[94:95], v[96:97]
	v_cvt_pk_bf16_f32 v100, v88, v89
	v_cvt_pk_bf16_f32 v101, v90, v91
	v_cvt_pk_bf16_f32 v102, v92, v93
	v_cvt_pk_bf16_f32 v103, v94, v95
	global_store_dwordx4 v[30:31], v[100:103], off offset:128
	v_xor_b32_e32 v83, 8, v28
	v_lshl_add_u32 v83, v83, 3, v26
	ds_read_b64 v[72:73], v83 offset:32768
	v_xor_b32_e32 v84, 9, v28
	v_lshl_add_u32 v84, v84, 3, v26
	ds_read_b64 v[74:75], v84 offset:32768
	ds_read_b32 v76, v27 offset:1024
	s_waitcnt lgkmcnt(3)
	v_div_scale_f32 v154, s[8:9], v82, v82, 1.0
	v_rcp_f32_e32 v155, v154
	v_lshlrev_b32_e32 v88, 16, v78
	v_and_b32_e32 v89, 0xffff0000, v78
	v_fma_f32 v156, -v154, v155, 1.0
	v_fmac_f32_e32 v155, v156, v155
	v_div_scale_f32 v156, vcc, 1.0, v82, 1.0
	v_mul_f32_e32 v157, v156, v155
	v_fma_f32 v158, -v154, v157, v156
	v_fmac_f32_e32 v157, v158, v155
	v_fma_f32 v154, -v154, v157, v156
	v_div_fmas_f32 v154, v154, v155, v157
	v_div_fixup_f32 v160, v154, v82, 1.0
	v_lshlrev_b32_e32 v90, 16, v79
	v_and_b32_e32 v91, 0xffff0000, v79
	v_lshlrev_b32_e32 v92, 16, v80
	v_and_b32_e32 v93, 0xffff0000, v80
	v_lshlrev_b32_e32 v94, 16, v81
	v_and_b32_e32 v95, 0xffff0000, v81
	v_pk_mul_f32 v[88:89], v[160:161], v[88:89] op_sel_hi:[0,1]
	v_pk_mul_f32 v[90:91], v[160:161], v[90:91] op_sel_hi:[0,1]
	v_pk_mul_f32 v[92:93], v[160:161], v[92:93] op_sel_hi:[0,1]
	v_pk_mul_f32 v[94:95], v[160:161], v[94:95] op_sel_hi:[0,1]
	s_waitcnt vmcnt(7)
	v_lshlrev_b32_e32 v96, 16, v52
	v_and_b32_e32 v97, 0xffff0000, v52
	v_pk_mul_f32 v[88:89], v[88:89], v[96:97]
	v_lshlrev_b32_e32 v96, 16, v53
	v_and_b32_e32 v97, 0xffff0000, v53
	v_pk_mul_f32 v[90:91], v[90:91], v[96:97]
	v_lshlrev_b32_e32 v96, 16, v54
	v_and_b32_e32 v97, 0xffff0000, v54
	v_pk_mul_f32 v[92:93], v[92:93], v[96:97]
	v_lshlrev_b32_e32 v96, 16, v55
	v_and_b32_e32 v97, 0xffff0000, v55
	v_pk_mul_f32 v[94:95], v[94:95], v[96:97]
	v_cvt_pk_bf16_f32 v104, v88, v89
	v_cvt_pk_bf16_f32 v105, v90, v91
	v_cvt_pk_bf16_f32 v106, v92, v93
	v_cvt_pk_bf16_f32 v107, v94, v95
	global_store_dwordx4 v[36:37], v[104:107], off offset:128
	v_xor_b32_e32 v83, 12, v28
	v_lshl_add_u32 v83, v83, 3, v26
	ds_read_b64 v[78:79], v83 offset:40960
	v_xor_b32_e32 v84, 13, v28
	v_lshl_add_u32 v84, v84, 3, v26
	ds_read_b64 v[80:81], v84 offset:40960
	ds_read_b32 v82, v27 offset:1280
	s_waitcnt lgkmcnt(3)
; #define LAS __attribute__((address_space(3)))
; __device__ __forceinline__ unsigned pkbf(float lo, float hi) { f32x2v v = {lo, hi}; return __builtin_bit_cast(unsigned, __builtin_convertvector(v, bf2_t)); }
; __device__ __forceinline__ float bflo(unsigned w) { return __uint_as_float(w << 16); }
; __device__ __forceinline__ float bfhi(unsigned w) { return __uint_as_float(w & 0xffff0000u); }
; template <int MIX, bool DRY = false>
; __device__ __forceinline__ void attn_phase(LAS unsigned char* lds, const bf16_t* Qb, const bf16_t* Kb, const bf16_t* Vb, bf16_t* Gb, const float* qg, const float* kg, const float* sinks) {
;     ...
;                 const int item = it * 512 + tidu, row = item >> 3, dg = item & 7, hr = row / CT, tl = row % CT;
;                 const int f = ((tl >> 1) ^ (tl >> 4) ^ (hr << 2)) & 15, head = kvh * REP + hr;
;                 const LAS unsigned char* orow = Oacc + row * 128;
;                 const u32x2 o0 = *(const LAS u32x2*)(orow + (((2 * dg) ^ f) << 3)), o1 = *(const LAS u32x2*)(orow + (((2 * dg + 1) ^ f) << 3));
;                 const float inv = 1.0f / lacc[row];
;                 u32x4* gp = (u32x4*)(Gb + (rowb + t0 + tl) * 1024 + head * 64 + 8 * dg);
;                 const u32x4 gv = *gp;
;                 u32x4 w;
;                 w.x = pkbf(bflo(o0.x) * inv * bflo(gv.x), bfhi(o0.x) * inv * bfhi(gv.x)); w.y = pkbf(bflo(o0.y) * inv * bflo(gv.y), bfhi(o0.y) * inv * bfhi(gv.y));
;                 w.z = pkbf(bflo(o1.x) * inv * bflo(gv.z), bfhi(o1.x) * inv * bfhi(gv.z)); w.w = pkbf(bflo(o1.y) * inv * bflo(gv.w), bfhi(o1.y) * inv * bfhi(gv.w));
;                 *gp = w;
;             }
;             if (more) STAGE_STORE(0)
	v_div_scale_f32 v154, s[8:9], v76, v76, 1.0
	v_rcp_f32_e32 v155, v154
	v_lshlrev_b32_e32 v88, 16, v72
	v_and_b32_e32 v89, 0xffff0000, v72
	v_fma_f32 v156, -v154, v155, 1.0
	v_fmac_f32_e32 v155, v156, v155
	v_div_scale_f32 v156, vcc, 1.0, v76, 1.0
	v_mul_f32_e32 v157, v156, v155
	v_fma_f32 v158, -v154, v157, v156
	v_fmac_f32_e32 v157, v158, v155
	v_fma_f32 v154, -v154, v157, v156
	v_div_fmas_f32 v154, v154, v155, v157
	v_div_fixup_f32 v160, v154, v76, 1.0
	v_lshlrev_b32_e32 v90, 16, v73
	v_and_b32_e32 v91, 0xffff0000, v73
	v_lshlrev_b32_e32 v92, 16, v74
	v_and_b32_e32 v93, 0xffff0000, v74
	v_lshlrev_b32_e32 v94, 16, v75
	v_and_b32_e32 v95, 0xffff0000, v75
	v_pk_mul_f32 v[88:89], v[160:161], v[88:89] op_sel_hi:[0,1]
	v_pk_mul_f32 v[90:91], v[160:161], v[90:91] op_sel_hi:[0,1]
	v_pk_mul_f32 v[92:93], v[160:161], v[92:93] op_sel_hi:[0,1]
	v_pk_mul_f32 v[94:95], v[160:161], v[94:95] op_sel_hi:[0,1]
	s_waitcnt vmcnt(7)
	v_lshlrev_b32_e32 v96, 16, v56
	v_and_b32_e32 v97, 0xffff0000, v56
	v_pk_mul_f32 v[88:89], v[88:89], v[96:97]
	v_lshlrev_b32_e32 v96, 16, v57
	v_and_b32_e32 v97, 0xffff0000, v57
	v_pk_mul_f32 v[90:91], v[90:91], v[96:97]
	v_lshlrev_b32_e32 v96, 16, v58
	v_and_b32_e32 v97, 0xffff0000, v58
	v_pk_mul_f32 v[92:93], v[92:93], v[96:97]
	v_lshlrev_b32_e32 v96, 16, v59
	v_and_b32_e32 v97, 0xffff0000, v59
	v_pk_mul_f32 v[94:95], v[94:95], v[96:97]
	v_cvt_pk_bf16_f32 v100, v88, v89
	v_cvt_pk_bf16_f32 v101, v90, v91
	v_cvt_pk_bf16_f32 v102, v92, v93
	v_cvt_pk_bf16_f32 v103, v94, v95
	global_store_dwordx4 v[30:31], v[100:103], off offset:256
	v_xor_b32_e32 v83, 12, v28
	v_lshl_add_u32 v83, v83, 3, v26
	ds_read_b64 v[72:73], v83 offset:49152
	v_xor_b32_e32 v84, 13, v28
	v_lshl_add_u32 v84, v84, 3, v26
	ds_read_b64 v[74:75], v84 offset:49152
	ds_read_b32 v76, v27 offset:1536
	s_waitcnt lgkmcnt(3)
	v_div_scale_f32 v154, s[8:9], v82, v82, 1.0
	v_rcp_f32_e32 v155, v154
	v_lshlrev_b32_e32 v88, 16, v78
	v_and_b32_e32 v89, 0xffff0000, v78
	v_fma_f32 v156, -v154, v155, 1.0
	v_fmac_f32_e32 v155, v156, v155
	v_div_scale_f32 v156, vcc, 1.0, v82, 1.0
	v_mul_f32_e32 v157, v156, v155
	v_fma_f32 v158, -v154, v157, v156
	v_fmac_f32_e32 v157, v158, v155
	v_fma_f32 v154, -v154, v157, v156
	v_div_fmas_f32 v154, v154, v155, v157
	v_div_fixup_f32 v160, v154, v82, 1.0
	v_lshlrev_b32_e32 v90, 16, v79
	v_and_b32_e32 v91, 0xffff0000, v79
	v_lshlrev_b32_e32 v92, 16, v80
	v_and_b32_e32 v93, 0xffff0000, v80
	v_lshlrev_b32_e32 v94, 16, v81
	v_and_b32_e32 v95, 0xffff0000, v81
	v_pk_mul_f32 v[88:89], v[160:161], v[88:89] op_sel_hi:[0,1]
	v_pk_mul_f32 v[90:91], v[160:161], v[90:91] op_sel_hi:[0,1]
	v_pk_mul_f32 v[92:93], v[160:161], v[92:93] op_sel_hi:[0,1]
	v_pk_mul_f32 v[94:95], v[160:161], v[94:95] op_sel_hi:[0,1]
	s_waitcnt vmcnt(7)
	v_lshlrev_b32_e32 v96, 16, v60
	v_and_b32_e32 v97, 0xffff0000, v60
	v_pk_mul_f32 v[88:89], v[88:89], v[96:97]
	v_lshlrev_b32_e32 v96, 16, v61
	v_and_b32_e32 v97, 0xffff0000, v61
	v_pk_mul_f32 v[90:91], v[90:91], v[96:97]
	v_lshlrev_b32_e32 v96, 16, v62
	v_and_b32_e32 v97, 0xffff0000, v62
	v_pk_mul_f32 v[92:93], v[92:93], v[96:97]
	v_lshlrev_b32_e32 v96, 16, v63
	v_and_b32_e32 v97, 0xffff0000, v63
	v_pk_mul_f32 v[94:95], v[94:95], v[96:97]
	v_cvt_pk_bf16_f32 v104, v88, v89
	v_cvt_pk_bf16_f32 v105, v90, v91
	v_cvt_pk_bf16_f32 v106, v92, v93
	v_cvt_pk_bf16_f32 v107, v94, v95
	global_store_dwordx4 v[36:37], v[104:107], off offset:256
	v_xor_b32_e32 v83, 8, v28
	v_lshl_add_u32 v83, v83, 3, v26
	ds_read_b64 v[78:79], v83 offset:57344
	v_xor_b32_e32 v84, 9, v28
	v_lshl_add_u32 v84, v84, 3, v26
	ds_read_b64 v[80:81], v84 offset:57344
	ds_read_b32 v82, v27 offset:1792
	s_waitcnt lgkmcnt(3)
	v_div_scale_f32 v154, s[8:9], v76, v76, 1.0
	v_rcp_f32_e32 v155, v154
	v_lshlrev_b32_e32 v88, 16, v72
	v_and_b32_e32 v89, 0xffff0000, v72
	v_fma_f32 v156, -v154, v155, 1.0
	v_fmac_f32_e32 v155, v156, v155
	v_div_scale_f32 v156, vcc, 1.0, v76, 1.0
	v_mul_f32_e32 v157, v156, v155
	v_fma_f32 v158, -v154, v157, v156
	v_fmac_f32_e32 v157, v158, v155
	v_fma_f32 v154, -v154, v157, v156
	v_div_fmas_f32 v154, v154, v155, v157
	v_div_fixup_f32 v160, v154, v76, 1.0
	v_lshlrev_b32_e32 v90, 16, v73
	v_and_b32_e32 v91, 0xffff0000, v73
	v_lshlrev_b32_e32 v92, 16, v74
	v_and_b32_e32 v93, 0xffff0000, v74
	v_lshlrev_b32_e32 v94, 16, v75
	v_and_b32_e32 v95, 0xffff0000, v75
	v_pk_mul_f32 v[88:89], v[160:161], v[88:89] op_sel_hi:[0,1]
	v_pk_mul_f32 v[90:91], v[160:161], v[90:91] op_sel_hi:[0,1]
	v_pk_mul_f32 v[92:93], v[160:161], v[92:93] op_sel_hi:[0,1]
	v_pk_mul_f32 v[94:95], v[160:161], v[94:95] op_sel_hi:[0,1]
	s_waitcnt vmcnt(7)
	v_lshlrev_b32_e32 v96, 16, v64
	v_and_b32_e32 v97, 0xffff0000, v64
	v_pk_mul_f32 v[88:89], v[88:89], v[96:97]
	v_lshlrev_b32_e32 v96, 16, v65
	v_and_b32_e32 v97, 0xffff0000, v65
	v_pk_mul_f32 v[90:91], v[90:91], v[96:97]
	v_lshlrev_b32_e32 v96, 16, v66
	v_and_b32_e32 v97, 0xffff0000, v66
	v_pk_mul_f32 v[92:93], v[92:93], v[96:97]
	v_lshlrev_b32_e32 v96, 16, v67
	v_and_b32_e32 v97, 0xffff0000, v67
	v_pk_mul_f32 v[94:95], v[94:95], v[96:97]
	v_cvt_pk_bf16_f32 v100, v88, v89
	v_cvt_pk_bf16_f32 v101, v90, v91
	v_cvt_pk_bf16_f32 v102, v92, v93
	v_cvt_pk_bf16_f32 v103, v94, v95
	global_store_dwordx4 v[30:31], v[100:103], off offset:384
	s_waitcnt lgkmcnt(0)
	v_div_scale_f32 v154, s[8:9], v82, v82, 1.0
	v_rcp_f32_e32 v155, v154
	v_lshlrev_b32_e32 v88, 16, v78
	v_and_b32_e32 v89, 0xffff0000, v78
	v_fma_f32 v156, -v154, v155, 1.0
	v_fmac_f32_e32 v155, v156, v155
	v_div_scale_f32 v156, vcc, 1.0, v82, 1.0
	v_mul_f32_e32 v157, v156, v155
	v_fma_f32 v158, -v154, v157, v156
	v_fmac_f32_e32 v157, v158, v155
	v_fma_f32 v154, -v154, v157, v156
	v_div_fmas_f32 v154, v154, v155, v157
	v_div_fixup_f32 v160, v154, v82, 1.0
	v_lshlrev_b32_e32 v90, 16, v79
	v_and_b32_e32 v91, 0xffff0000, v79
	v_lshlrev_b32_e32 v92, 16, v80
	v_and_b32_e32 v93, 0xffff0000, v80
	v_lshlrev_b32_e32 v94, 16, v81
	v_and_b32_e32 v95, 0xffff0000, v81
	v_pk_mul_f32 v[88:89], v[160:161], v[88:89] op_sel_hi:[0,1]
	v_pk_mul_f32 v[90:91], v[160:161], v[90:91] op_sel_hi:[0,1]
	v_pk_mul_f32 v[92:93], v[160:161], v[92:93] op_sel_hi:[0,1]
	v_pk_mul_f32 v[94:95], v[160:161], v[94:95] op_sel_hi:[0,1]
	s_waitcnt vmcnt(7)
	v_lshlrev_b32_e32 v96, 16, v68
	v_and_b32_e32 v97, 0xffff0000, v68
	v_pk_mul_f32 v[88:89], v[88:89], v[96:97]
	v_lshlrev_b32_e32 v96, 16, v69
	v_and_b32_e32 v97, 0xffff0000, v69
	v_pk_mul_f32 v[90:91], v[90:91], v[96:97]
	v_lshlrev_b32_e32 v96, 16, v70
	v_and_b32_e32 v97, 0xffff0000, v70
	v_pk_mul_f32 v[92:93], v[92:93], v[96:97]
	v_lshlrev_b32_e32 v96, 16, v71
	v_and_b32_e32 v97, 0xffff0000, v71
	v_pk_mul_f32 v[94:95], v[94:95], v[96:97]
	v_cvt_pk_bf16_f32 v104, v88, v89
	v_cvt_pk_bf16_f32 v105, v90, v91
	v_cvt_pk_bf16_f32 v106, v92, v93
	v_cvt_pk_bf16_f32 v107, v94, v95
	global_store_dwordx4 v[36:37], v[104:107], off offset:384
	v_readlane_b32 s82, v251, 47
	s_mov_b64 s[4:5], -1
	s_and_b64 vcc, exec, s[0:1]
	v_readlane_b32 s83, v251, 48
	v_readlane_b32 s91, v251, 49
	s_cbranch_vccz .LBB0_407
; template <int MIX, bool DRY = false>
; __device__ __forceinline__ void attn_phase(LAS unsigned char* lds, const bf16_t* Qb, const bf16_t* Kb, const bf16_t* Vb, bf16_t* Gb, const float* qg, const float* kg, const float* sinks) {
;     ...
;             if (more) STAGE_STORE(0)
	ds_write_b128 v237, v[114:117]
	ds_write_b128 v238, v[118:121]
	ds_write_b128 v237, v[122:125] offset:8192
	ds_write_b128 v238, v[126:129] offset:8192
	ds_write_b128 v237, v[130:133] offset:16384
	ds_write_b128 v238, v[134:137] offset:16384
	ds_write_b128 v237, v[138:141] offset:24576
	ds_write_b128 v238, v[142:145] offset:24576
	s_branch .LBB0_406
